# grid barrier: waiting workgroups poll the top-level generation word directly instead of the per-XCD republished word
# speedup vs baseline: 1.0129x; 1.0009x over previous
; __device__ __forceinline__ unsigned xb_ld(unsigned* p)              { return __hip_atomic_load(p, __ATOMIC_RELAXED, __HIP_MEMORY_SCOPE_AGENT); }
; __device__ __forceinline__ unsigned xb_add(unsigned* p, unsigned v) { return __hip_atomic_fetch_add(p, v, __ATOMIC_RELAXED, __HIP_MEMORY_SCOPE_AGENT); }
; #define XB_SPIN(cond, bar) do { unsigned _sp = 0; while (cond) { __builtin_amdgcn_s_sleep(1); \
;     if ((++_sp & 255u) == 0u) { if (xb_ld(&(bar)[XB_TMO])) break; if (_sp > XB_SPIN_CAP) { atomicAdd(&(bar)[XB_TMO], 1u); break; } } } } while (0)
; __device__ __forceinline__ void xcd_barrier(const XcdBarrier& b) {
;     ...
;         const unsigned old = xb_add(&bar[XB_XSUB(b.x)], 1u);
;         const unsigned gen = old / nloc;
;         if (old + 1u == (gen + 1u) * nloc) {
;             __builtin_amdgcn_fence(__ATOMIC_RELEASE, "agent");
;             asm volatile("s_waitcnt vmcnt(0)" ::: "memory");
;             const unsigned og = xb_add(&bar[XB_TOP], 1u);
;             const unsigned tg = og / nx;
;             if (og + 1u == (tg + 1u) * nx) xb_add(&bar[XB_TOPGEN], 1u);
;             else XB_SPIN(xb_ld(&bar[XB_TOPGEN]) == tg, bar);
;             __builtin_amdgcn_fence(__ATOMIC_ACQUIRE, "agent");
;             xb_add(&bar[XB_XGEN(b.x)], 1u);
;             asm volatile("s_waitcnt vmcnt(0)" ::: "memory");
;         } else {
;             XB_SPIN(xb_ld(&bar[XB_XGEN(b.x)]) == gen, bar);
;             __builtin_amdgcn_fence(__ATOMIC_ACQUIRE, "agent");
.LBB0_109:
	s_or_b64 exec, exec, s[8:9]
	v_cvt_f32_u32_e32 v6, v4
	s_waitcnt vmcnt(0)
	v_readfirstlane_b32 s3, v5
	v_sub_u32_e32 v5, 0, v4
	v_rcp_iflag_f32_e32 v6, v6
	v_add_u32_e32 v7, s3, v3
	v_mul_f32_e32 v6, 0x4f7ffffe, v6
	v_cvt_u32_f32_e32 v6, v6
	v_mul_lo_u32 v3, v5, v6
	v_mul_hi_u32 v3, v6, v3
	v_add_u32_e32 v3, v6, v3
	v_mul_hi_u32 v3, v7, v3
	v_mul_lo_u32 v5, v3, v4
	v_sub_u32_e32 v5, v7, v5
	v_add_u32_e32 v6, 1, v3
	v_cmp_ge_u32_e32 vcc, v5, v4
	s_nop 1
	v_cndmask_b32_e32 v3, v3, v6, vcc
	v_sub_u32_e32 v6, v5, v4
	v_cndmask_b32_e32 v5, v5, v6, vcc
	v_add_u32_e32 v6, 1, v3
	v_cmp_ge_u32_e32 vcc, v5, v4
	v_add_u32_e32 v5, 1, v7
	s_nop 0
	v_cndmask_b32_e32 v3, v3, v6, vcc
	v_mul_lo_u32 v6, v4, v3
	v_add_u32_e32 v4, v6, v4
	v_cmp_ne_u32_e32 vcc, v5, v4
	s_and_saveexec_b64 s[6:7], vcc
	s_xor_b64 s[6:7], exec, s[6:7]
	s_cbranch_execz .LBB0_123
	s_waitcnt lgkmcnt(0)
	v_mov_b32_e32 v2, 0x7100
	global_load_dword v2, v2, s[78:79] offset:1024 sc1
	s_add_u32 s12, s78, 0x7500
	s_addc_u32 s13, s79, 0
	s_waitcnt vmcnt(0)
	v_cmp_eq_u32_e32 vcc, v2, v3
	s_and_saveexec_b64 s[8:9], vcc
	s_cbranch_execz .LBB0_122
	s_add_u32 s10, s78, 0x4200
	s_addc_u32 s11, s79, 0
	s_mov_b32 s3, 1
	s_mov_b64 s[14:15], 0
	v_mov_b32_e32 v2, 0
	s_branch .LBB0_113

; __device__ __forceinline__ unsigned xb_ld(unsigned* p)              { return __hip_atomic_load(p, __ATOMIC_RELAXED, __HIP_MEMORY_SCOPE_AGENT); }
; __device__ __forceinline__ unsigned xb_add(unsigned* p, unsigned v) { return __hip_atomic_fetch_add(p, v, __ATOMIC_RELAXED, __HIP_MEMORY_SCOPE_AGENT); }
; #define XB_SPIN(cond, bar) do { unsigned _sp = 0; while (cond) { __builtin_amdgcn_s_sleep(1); \
;     if ((++_sp & 255u) == 0u) { if (xb_ld(&(bar)[XB_TMO])) break; if (_sp > XB_SPIN_CAP) { atomicAdd(&(bar)[XB_TMO], 1u); break; } } } } while (0)
; __device__ __forceinline__ void xcd_barrier(const XcdBarrier& b) {
;     ...
;         const unsigned old = xb_add(&bar[XB_XSUB(b.x)], 1u);
;         const unsigned gen = old / nloc;
;         if (old + 1u == (gen + 1u) * nloc) {
;             __builtin_amdgcn_fence(__ATOMIC_RELEASE, "agent");
;             asm volatile("s_waitcnt vmcnt(0)" ::: "memory");
;             const unsigned og = xb_add(&bar[XB_TOP], 1u);
;             const unsigned tg = og / nx;
;             if (og + 1u == (tg + 1u) * nx) xb_add(&bar[XB_TOPGEN], 1u);
;             else XB_SPIN(xb_ld(&bar[XB_TOPGEN]) == tg, bar);
;             __builtin_amdgcn_fence(__ATOMIC_ACQUIRE, "agent");
;             xb_add(&bar[XB_XGEN(b.x)], 1u);
;             asm volatile("s_waitcnt vmcnt(0)" ::: "memory");
;         } else {
;             XB_SPIN(xb_ld(&bar[XB_XGEN(b.x)]) == gen, bar);
;             __builtin_amdgcn_fence(__ATOMIC_ACQUIRE, "agent");
.LBB0_552:
	s_or_b64 exec, exec, s[10:11]
	v_cvt_f32_u32_e32 v6, v4
	s_waitcnt vmcnt(0)
	v_readfirstlane_b32 s8, v5
	v_sub_u32_e32 v5, 0, v4
	v_rcp_iflag_f32_e32 v6, v6
	v_add_u32_e32 v7, s8, v3
	v_mul_f32_e32 v6, 0x4f7ffffe, v6
	v_cvt_u32_f32_e32 v6, v6
	v_mul_lo_u32 v3, v5, v6
	v_mul_hi_u32 v3, v6, v3
	v_add_u32_e32 v3, v6, v3
	v_mul_hi_u32 v3, v7, v3
	v_mul_lo_u32 v5, v3, v4
	v_sub_u32_e32 v5, v7, v5
	v_add_u32_e32 v6, 1, v3
	v_cmp_ge_u32_e32 vcc, v5, v4
	s_nop 1
	v_cndmask_b32_e32 v3, v3, v6, vcc
	v_sub_u32_e32 v6, v5, v4
	v_cndmask_b32_e32 v5, v5, v6, vcc
	v_add_u32_e32 v6, 1, v3
	v_cmp_ge_u32_e32 vcc, v5, v4
	v_add_u32_e32 v5, 1, v7
	s_nop 0
	v_cndmask_b32_e32 v3, v3, v6, vcc
	v_mul_lo_u32 v6, v4, v3
	v_add_u32_e32 v4, v6, v4
	v_cmp_ne_u32_e32 vcc, v5, v4
	s_and_saveexec_b64 s[8:9], vcc
	s_xor_b64 s[8:9], exec, s[8:9]
	s_cbranch_execz .LBB0_566
	s_waitcnt lgkmcnt(0)
	v_mov_b32_e32 v2, 0x7100
	global_load_dword v2, v2, s[78:79] offset:1024 sc1
	s_add_u32 s18, s78, 0x7500
	s_addc_u32 s19, s79, 0
	s_waitcnt vmcnt(0)
	v_cmp_eq_u32_e32 vcc, v2, v3
	s_and_saveexec_b64 s[10:11], vcc
	s_cbranch_execz .LBB0_565
	s_add_u32 s12, s78, 0x4200
	s_addc_u32 s13, s79, 0
	s_mov_b32 s30, 1
	s_mov_b64 s[20:21], 0
	v_mov_b32_e32 v2, 0
	s_branch .LBB0_556

; __device__ __forceinline__ unsigned xb_ld(unsigned* p)              { return __hip_atomic_load(p, __ATOMIC_RELAXED, __HIP_MEMORY_SCOPE_AGENT); }
; __device__ __forceinline__ unsigned xb_add(unsigned* p, unsigned v) { return __hip_atomic_fetch_add(p, v, __ATOMIC_RELAXED, __HIP_MEMORY_SCOPE_AGENT); }
; #define XB_SPIN(cond, bar) do { unsigned _sp = 0; while (cond) { __builtin_amdgcn_s_sleep(1); \
;     if ((++_sp & 255u) == 0u) { if (xb_ld(&(bar)[XB_TMO])) break; if (_sp > XB_SPIN_CAP) { atomicAdd(&(bar)[XB_TMO], 1u); break; } } } } while (0)
; __device__ __forceinline__ void xcd_barrier(const XcdBarrier& b) {
;     ...
;         const unsigned old = xb_add(&bar[XB_XSUB(b.x)], 1u);
;         const unsigned gen = old / nloc;
;         if (old + 1u == (gen + 1u) * nloc) {
;             __builtin_amdgcn_fence(__ATOMIC_RELEASE, "agent");
;             asm volatile("s_waitcnt vmcnt(0)" ::: "memory");
;             const unsigned og = xb_add(&bar[XB_TOP], 1u);
;             const unsigned tg = og / nx;
;             if (og + 1u == (tg + 1u) * nx) xb_add(&bar[XB_TOPGEN], 1u);
;             else XB_SPIN(xb_ld(&bar[XB_TOPGEN]) == tg, bar);
;             __builtin_amdgcn_fence(__ATOMIC_ACQUIRE, "agent");
;             xb_add(&bar[XB_XGEN(b.x)], 1u);
;             asm volatile("s_waitcnt vmcnt(0)" ::: "memory");
;         } else {
;             XB_SPIN(xb_ld(&bar[XB_XGEN(b.x)]) == gen, bar);
;             __builtin_amdgcn_fence(__ATOMIC_ACQUIRE, "agent");
.LBB0_658:
	s_or_b64 exec, exec, s[12:13]
	v_cvt_f32_u32_e32 v6, v4
	s_waitcnt vmcnt(0)
	v_readfirstlane_b32 s10, v5
	v_sub_u32_e32 v5, 0, v4
	v_rcp_iflag_f32_e32 v6, v6
	v_add_u32_e32 v7, s10, v3
	v_mul_f32_e32 v6, 0x4f7ffffe, v6
	v_cvt_u32_f32_e32 v6, v6
	v_mul_lo_u32 v3, v5, v6
	v_mul_hi_u32 v3, v6, v3
	v_add_u32_e32 v3, v6, v3
	v_mul_hi_u32 v3, v7, v3
	v_mul_lo_u32 v5, v3, v4
	v_sub_u32_e32 v5, v7, v5
	v_add_u32_e32 v6, 1, v3
	v_cmp_ge_u32_e32 vcc, v5, v4
	s_nop 1
	v_cndmask_b32_e32 v3, v3, v6, vcc
	v_sub_u32_e32 v6, v5, v4
	v_cndmask_b32_e32 v5, v5, v6, vcc
	v_add_u32_e32 v6, 1, v3
	v_cmp_ge_u32_e32 vcc, v5, v4
	v_add_u32_e32 v5, 1, v7
	s_nop 0
	v_cndmask_b32_e32 v3, v3, v6, vcc
	v_mul_lo_u32 v6, v4, v3
	v_add_u32_e32 v4, v6, v4
	v_cmp_ne_u32_e32 vcc, v5, v4
	s_and_saveexec_b64 s[10:11], vcc
	s_xor_b64 s[10:11], exec, s[10:11]
	s_cbranch_execz .LBB0_672
	s_waitcnt lgkmcnt(0)
	v_mov_b32_e32 v2, 0x7100
	global_load_dword v2, v2, s[78:79] offset:1024 sc1
	s_add_u32 s18, s78, 0x7500
	s_addc_u32 s19, s79, 0
	s_waitcnt vmcnt(0)
	v_cmp_eq_u32_e32 vcc, v2, v3
	s_and_saveexec_b64 s[12:13], vcc
	s_cbranch_execz .LBB0_671
	s_add_u32 s16, s78, 0x4200
	s_addc_u32 s17, s79, 0
	s_mov_b32 s30, 1
	s_mov_b64 s[20:21], 0
	v_mov_b32_e32 v2, 0
	s_branch .LBB0_662

; __device__ __forceinline__ unsigned xb_ld(unsigned* p)              { return __hip_atomic_load(p, __ATOMIC_RELAXED, __HIP_MEMORY_SCOPE_AGENT); }
; __device__ __forceinline__ unsigned xb_add(unsigned* p, unsigned v) { return __hip_atomic_fetch_add(p, v, __ATOMIC_RELAXED, __HIP_MEMORY_SCOPE_AGENT); }
; #define XB_SPIN(cond, bar) do { unsigned _sp = 0; while (cond) { __builtin_amdgcn_s_sleep(1); \
;     if ((++_sp & 255u) == 0u) { if (xb_ld(&(bar)[XB_TMO])) break; if (_sp > XB_SPIN_CAP) { atomicAdd(&(bar)[XB_TMO], 1u); break; } } } } while (0)
; __device__ __forceinline__ void xcd_barrier(const XcdBarrier& b) {
;     ...
;         const unsigned old = xb_add(&bar[XB_XSUB(b.x)], 1u);
;         const unsigned gen = old / nloc;
;         if (old + 1u == (gen + 1u) * nloc) {
;             __builtin_amdgcn_fence(__ATOMIC_RELEASE, "agent");
;             asm volatile("s_waitcnt vmcnt(0)" ::: "memory");
;             const unsigned og = xb_add(&bar[XB_TOP], 1u);
;             const unsigned tg = og / nx;
;             if (og + 1u == (tg + 1u) * nx) xb_add(&bar[XB_TOPGEN], 1u);
;             else XB_SPIN(xb_ld(&bar[XB_TOPGEN]) == tg, bar);
;             __builtin_amdgcn_fence(__ATOMIC_ACQUIRE, "agent");
;             xb_add(&bar[XB_XGEN(b.x)], 1u);
;             asm volatile("s_waitcnt vmcnt(0)" ::: "memory");
;         } else {
;             XB_SPIN(xb_ld(&bar[XB_XGEN(b.x)]) == gen, bar);
;             __builtin_amdgcn_fence(__ATOMIC_ACQUIRE, "agent");
.LBB0_971:
	s_or_b64 exec, exec, s[10:11]
	v_cvt_f32_u32_e32 v6, v4
	s_waitcnt vmcnt(0)
	v_readfirstlane_b32 s3, v5
	v_sub_u32_e32 v5, 0, v4
	v_rcp_iflag_f32_e32 v6, v6
	v_add_u32_e32 v7, s3, v3
	v_mul_f32_e32 v6, 0x4f7ffffe, v6
	v_cvt_u32_f32_e32 v6, v6
	v_mul_lo_u32 v3, v5, v6
	v_mul_hi_u32 v3, v6, v3
	v_add_u32_e32 v3, v6, v3
	v_mul_hi_u32 v3, v7, v3
	v_mul_lo_u32 v5, v3, v4
	v_sub_u32_e32 v5, v7, v5
	v_add_u32_e32 v6, 1, v3
	v_cmp_ge_u32_e32 vcc, v5, v4
	s_nop 1
	v_cndmask_b32_e32 v3, v3, v6, vcc
	v_sub_u32_e32 v6, v5, v4
	v_cndmask_b32_e32 v5, v5, v6, vcc
	v_add_u32_e32 v6, 1, v3
	v_cmp_ge_u32_e32 vcc, v5, v4
	v_add_u32_e32 v5, 1, v7
	s_nop 0
	v_cndmask_b32_e32 v3, v3, v6, vcc
	v_mul_lo_u32 v6, v4, v3
	v_add_u32_e32 v4, v6, v4
	v_cmp_ne_u32_e32 vcc, v5, v4
	s_and_saveexec_b64 s[8:9], vcc
	s_xor_b64 s[8:9], exec, s[8:9]
	s_cbranch_execz .LBB0_985
	s_waitcnt lgkmcnt(0)
	v_mov_b32_e32 v2, 0x7100
	global_load_dword v2, v2, s[78:79] offset:1024 sc1
	s_add_u32 s14, s78, 0x7500
	s_addc_u32 s15, s79, 0
	s_waitcnt vmcnt(0)
	v_cmp_eq_u32_e32 vcc, v2, v3
	s_and_saveexec_b64 s[10:11], vcc
	s_cbranch_execz .LBB0_984
	s_add_u32 s12, s78, 0x4200
	s_addc_u32 s13, s79, 0
	s_mov_b32 s3, 1
	s_mov_b64 s[16:17], 0
	v_mov_b32_e32 v2, 0
	s_branch .LBB0_975

; __device__ __forceinline__ unsigned xb_ld(unsigned* p)              { return __hip_atomic_load(p, __ATOMIC_RELAXED, __HIP_MEMORY_SCOPE_AGENT); }
; __device__ __forceinline__ unsigned xb_add(unsigned* p, unsigned v) { return __hip_atomic_fetch_add(p, v, __ATOMIC_RELAXED, __HIP_MEMORY_SCOPE_AGENT); }
; #define XB_SPIN(cond, bar) do { unsigned _sp = 0; while (cond) { __builtin_amdgcn_s_sleep(1); \
;     if ((++_sp & 255u) == 0u) { if (xb_ld(&(bar)[XB_TMO])) break; if (_sp > XB_SPIN_CAP) { atomicAdd(&(bar)[XB_TMO], 1u); break; } } } } while (0)
; __device__ __forceinline__ void xcd_barrier(const XcdBarrier& b) {
;     ...
;         const unsigned old = xb_add(&bar[XB_XSUB(b.x)], 1u);
;         const unsigned gen = old / nloc;
;         if (old + 1u == (gen + 1u) * nloc) {
;             __builtin_amdgcn_fence(__ATOMIC_RELEASE, "agent");
;             asm volatile("s_waitcnt vmcnt(0)" ::: "memory");
;             const unsigned og = xb_add(&bar[XB_TOP], 1u);
;             const unsigned tg = og / nx;
;             if (og + 1u == (tg + 1u) * nx) xb_add(&bar[XB_TOPGEN], 1u);
;             else XB_SPIN(xb_ld(&bar[XB_TOPGEN]) == tg, bar);
;             __builtin_amdgcn_fence(__ATOMIC_ACQUIRE, "agent");
;             xb_add(&bar[XB_XGEN(b.x)], 1u);
;             asm volatile("s_waitcnt vmcnt(0)" ::: "memory");
;         } else {
;             XB_SPIN(xb_ld(&bar[XB_XGEN(b.x)]) == gen, bar);
;             __builtin_amdgcn_fence(__ATOMIC_ACQUIRE, "agent");
.LBB0_1138:
	s_or_b64 exec, exec, s[12:13]
	v_cvt_f32_u32_e32 v6, v4
	s_waitcnt vmcnt(0)
	v_readfirstlane_b32 s3, v5
	v_sub_u32_e32 v5, 0, v4
	v_rcp_iflag_f32_e32 v6, v6
	v_add_u32_e32 v7, s3, v3
	v_mul_f32_e32 v6, 0x4f7ffffe, v6
	v_cvt_u32_f32_e32 v6, v6
	v_mul_lo_u32 v3, v5, v6
	v_mul_hi_u32 v3, v6, v3
	v_add_u32_e32 v3, v6, v3
	v_mul_hi_u32 v3, v7, v3
	v_mul_lo_u32 v5, v3, v4
	v_sub_u32_e32 v5, v7, v5
	v_add_u32_e32 v6, 1, v3
	v_cmp_ge_u32_e32 vcc, v5, v4
	s_nop 1
	v_cndmask_b32_e32 v3, v3, v6, vcc
	v_sub_u32_e32 v6, v5, v4
	v_cndmask_b32_e32 v5, v5, v6, vcc
	v_add_u32_e32 v6, 1, v3
	v_cmp_ge_u32_e32 vcc, v5, v4
	v_add_u32_e32 v5, 1, v7
	s_nop 0
	v_cndmask_b32_e32 v3, v3, v6, vcc
	v_mul_lo_u32 v6, v4, v3
	v_add_u32_e32 v4, v6, v4
	v_cmp_ne_u32_e32 vcc, v5, v4
	s_and_saveexec_b64 s[8:9], vcc
	s_xor_b64 s[8:9], exec, s[8:9]
	s_cbranch_execz .LBB0_1152
	s_waitcnt lgkmcnt(0)
	v_mov_b32_e32 v2, 0x7100
	global_load_dword v2, v2, s[78:79] offset:1024 sc1
	s_add_u32 s16, s78, 0x7500
	s_addc_u32 s17, s79, 0
	s_waitcnt vmcnt(0)
	v_cmp_eq_u32_e32 vcc, v2, v3
	s_and_saveexec_b64 s[12:13], vcc
	s_cbranch_execz .LBB0_1151
	s_add_u32 s14, s78, 0x4200
	s_addc_u32 s15, s79, 0
	s_mov_b32 s3, 1
	s_mov_b64 s[18:19], 0
	v_mov_b32_e32 v2, 0
	s_branch .LBB0_1142

; __device__ __forceinline__ unsigned xb_ld(unsigned* p)              { return __hip_atomic_load(p, __ATOMIC_RELAXED, __HIP_MEMORY_SCOPE_AGENT); }
; __device__ __forceinline__ unsigned xb_add(unsigned* p, unsigned v) { return __hip_atomic_fetch_add(p, v, __ATOMIC_RELAXED, __HIP_MEMORY_SCOPE_AGENT); }
; #define XB_SPIN(cond, bar) do { unsigned _sp = 0; while (cond) { __builtin_amdgcn_s_sleep(1); \
;     if ((++_sp & 255u) == 0u) { if (xb_ld(&(bar)[XB_TMO])) break; if (_sp > XB_SPIN_CAP) { atomicAdd(&(bar)[XB_TMO], 1u); break; } } } } while (0)
; __device__ __forceinline__ void xcd_barrier(const XcdBarrier& b) {
;     ...
;         const unsigned old = xb_add(&bar[XB_XSUB(b.x)], 1u);
;         const unsigned gen = old / nloc;
;         if (old + 1u == (gen + 1u) * nloc) {
;             __builtin_amdgcn_fence(__ATOMIC_RELEASE, "agent");
;             asm volatile("s_waitcnt vmcnt(0)" ::: "memory");
;             const unsigned og = xb_add(&bar[XB_TOP], 1u);
;             const unsigned tg = og / nx;
;             if (og + 1u == (tg + 1u) * nx) xb_add(&bar[XB_TOPGEN], 1u);
;             else XB_SPIN(xb_ld(&bar[XB_TOPGEN]) == tg, bar);
;             __builtin_amdgcn_fence(__ATOMIC_ACQUIRE, "agent");
;             xb_add(&bar[XB_XGEN(b.x)], 1u);
;             asm volatile("s_waitcnt vmcnt(0)" ::: "memory");
;         } else {
;             XB_SPIN(xb_ld(&bar[XB_XGEN(b.x)]) == gen, bar);
;             __builtin_amdgcn_fence(__ATOMIC_ACQUIRE, "agent");
.LBB0_1425:
	s_or_b64 exec, exec, s[22:23]
	v_cvt_f32_u32_e32 v6, v4
	s_waitcnt vmcnt(0)
	v_readfirstlane_b32 s3, v5
	v_sub_u32_e32 v5, 0, v4
	v_rcp_iflag_f32_e32 v6, v6
	v_add_u32_e32 v7, s3, v3
	v_mul_f32_e32 v6, 0x4f7ffffe, v6
	v_cvt_u32_f32_e32 v6, v6
	v_mul_lo_u32 v3, v5, v6
	v_mul_hi_u32 v3, v6, v3
	v_add_u32_e32 v3, v6, v3
	v_mul_hi_u32 v3, v7, v3
	v_mul_lo_u32 v5, v3, v4
	v_sub_u32_e32 v5, v7, v5
	v_add_u32_e32 v6, 1, v3
	v_cmp_ge_u32_e32 vcc, v5, v4
	s_nop 1
	v_cndmask_b32_e32 v3, v3, v6, vcc
	v_sub_u32_e32 v6, v5, v4
	v_cndmask_b32_e32 v5, v5, v6, vcc
	v_add_u32_e32 v6, 1, v3
	v_cmp_ge_u32_e32 vcc, v5, v4
	v_add_u32_e32 v5, 1, v7
	s_nop 0
	v_cndmask_b32_e32 v3, v3, v6, vcc
	v_mul_lo_u32 v6, v4, v3
	v_add_u32_e32 v4, v6, v4
	v_cmp_ne_u32_e32 vcc, v5, v4
	s_and_saveexec_b64 s[20:21], vcc
	s_xor_b64 s[20:21], exec, s[20:21]
	s_cbranch_execz .LBB0_1439
	s_waitcnt lgkmcnt(0)
	v_mov_b32_e32 v2, 0x7100
	global_load_dword v2, v2, s[78:79] offset:1024 sc1
	s_add_u32 s26, s78, 0x7500
	s_addc_u32 s27, s79, 0
	s_waitcnt vmcnt(0)
	v_cmp_eq_u32_e32 vcc, v2, v3
	s_and_saveexec_b64 s[22:23], vcc
	s_cbranch_execz .LBB0_1438
	s_add_u32 s24, s78, 0x4200
	s_addc_u32 s25, s79, 0
	s_mov_b32 s3, 1
	s_mov_b64 s[28:29], 0
	v_mov_b32_e32 v2, 0
	s_branch .LBB0_1429

; __device__ __forceinline__ unsigned xb_ld(unsigned* p)              { return __hip_atomic_load(p, __ATOMIC_RELAXED, __HIP_MEMORY_SCOPE_AGENT); }
; __device__ __forceinline__ unsigned xb_add(unsigned* p, unsigned v) { return __hip_atomic_fetch_add(p, v, __ATOMIC_RELAXED, __HIP_MEMORY_SCOPE_AGENT); }
; #define XB_SPIN(cond, bar) do { unsigned _sp = 0; while (cond) { __builtin_amdgcn_s_sleep(1); \
;     if ((++_sp & 255u) == 0u) { if (xb_ld(&(bar)[XB_TMO])) break; if (_sp > XB_SPIN_CAP) { atomicAdd(&(bar)[XB_TMO], 1u); break; } } } } while (0)
; __device__ __forceinline__ void xcd_barrier(const XcdBarrier& b) {
;     ...
;         const unsigned old = xb_add(&bar[XB_XSUB(b.x)], 1u);
;         const unsigned gen = old / nloc;
;         if (old + 1u == (gen + 1u) * nloc) {
;             __builtin_amdgcn_fence(__ATOMIC_RELEASE, "agent");
;             asm volatile("s_waitcnt vmcnt(0)" ::: "memory");
;             const unsigned og = xb_add(&bar[XB_TOP], 1u);
;             const unsigned tg = og / nx;
;             if (og + 1u == (tg + 1u) * nx) xb_add(&bar[XB_TOPGEN], 1u);
;             else XB_SPIN(xb_ld(&bar[XB_TOPGEN]) == tg, bar);
;             __builtin_amdgcn_fence(__ATOMIC_ACQUIRE, "agent");
;             xb_add(&bar[XB_XGEN(b.x)], 1u);
;             asm volatile("s_waitcnt vmcnt(0)" ::: "memory");
;         } else {
;             XB_SPIN(xb_ld(&bar[XB_XGEN(b.x)]) == gen, bar);
;             __builtin_amdgcn_fence(__ATOMIC_ACQUIRE, "agent");
.LBB0_1504:
	s_or_b64 exec, exec, s[18:19]
	v_cvt_f32_u32_e32 v6, v4
	s_waitcnt vmcnt(0)
	v_readfirstlane_b32 s3, v5
	v_sub_u32_e32 v5, 0, v4
	v_rcp_iflag_f32_e32 v6, v6
	v_add_u32_e32 v7, s3, v3
	v_mul_f32_e32 v6, 0x4f7ffffe, v6
	v_cvt_u32_f32_e32 v6, v6
	v_mul_lo_u32 v3, v5, v6
	v_mul_hi_u32 v3, v6, v3
	v_add_u32_e32 v3, v6, v3
	v_mul_hi_u32 v3, v7, v3
	v_mul_lo_u32 v5, v3, v4
	v_sub_u32_e32 v5, v7, v5
	v_add_u32_e32 v6, 1, v3
	v_cmp_ge_u32_e32 vcc, v5, v4
	s_nop 1
	v_cndmask_b32_e32 v3, v3, v6, vcc
	v_sub_u32_e32 v6, v5, v4
	v_cndmask_b32_e32 v5, v5, v6, vcc
	v_add_u32_e32 v6, 1, v3
	v_cmp_ge_u32_e32 vcc, v5, v4
	v_add_u32_e32 v5, 1, v7
	s_nop 0
	v_cndmask_b32_e32 v3, v3, v6, vcc
	v_mul_lo_u32 v6, v4, v3
	v_add_u32_e32 v4, v6, v4
	v_cmp_ne_u32_e32 vcc, v5, v4
	s_and_saveexec_b64 s[8:9], vcc
	s_xor_b64 s[8:9], exec, s[8:9]
	s_cbranch_execz .LBB0_1518
	s_waitcnt lgkmcnt(0)
	v_mov_b32_e32 v2, 0x7100
	global_load_dword v2, v2, s[78:79] offset:1024 sc1
	s_add_u32 s22, s78, 0x7500
	s_addc_u32 s23, s79, 0
	s_waitcnt vmcnt(0)
	v_cmp_eq_u32_e32 vcc, v2, v3
	s_and_saveexec_b64 s[18:19], vcc
	s_cbranch_execz .LBB0_1517
	s_add_u32 s20, s78, 0x4200
	s_addc_u32 s21, s79, 0
	s_mov_b32 s3, 1
	s_mov_b64 s[24:25], 0
	v_mov_b32_e32 v2, 0
	s_branch .LBB0_1508

; __device__ __forceinline__ unsigned xb_ld(unsigned* p)              { return __hip_atomic_load(p, __ATOMIC_RELAXED, __HIP_MEMORY_SCOPE_AGENT); }
; __device__ __forceinline__ unsigned xb_add(unsigned* p, unsigned v) { return __hip_atomic_fetch_add(p, v, __ATOMIC_RELAXED, __HIP_MEMORY_SCOPE_AGENT); }
; #define XB_SPIN(cond, bar) do { unsigned _sp = 0; while (cond) { __builtin_amdgcn_s_sleep(1); \
;     if ((++_sp & 255u) == 0u) { if (xb_ld(&(bar)[XB_TMO])) break; if (_sp > XB_SPIN_CAP) { atomicAdd(&(bar)[XB_TMO], 1u); break; } } } } while (0)
; __device__ __forceinline__ void xcd_barrier(const XcdBarrier& b) {
;     ...
;         const unsigned old = xb_add(&bar[XB_XSUB(b.x)], 1u);
;         const unsigned gen = old / nloc;
;         if (old + 1u == (gen + 1u) * nloc) {
;             __builtin_amdgcn_fence(__ATOMIC_RELEASE, "agent");
;             asm volatile("s_waitcnt vmcnt(0)" ::: "memory");
;             const unsigned og = xb_add(&bar[XB_TOP], 1u);
;             const unsigned tg = og / nx;
;             if (og + 1u == (tg + 1u) * nx) xb_add(&bar[XB_TOPGEN], 1u);
;             else XB_SPIN(xb_ld(&bar[XB_TOPGEN]) == tg, bar);
;             __builtin_amdgcn_fence(__ATOMIC_ACQUIRE, "agent");
;             xb_add(&bar[XB_XGEN(b.x)], 1u);
;             asm volatile("s_waitcnt vmcnt(0)" ::: "memory");
;         } else {
;             XB_SPIN(xb_ld(&bar[XB_XGEN(b.x)]) == gen, bar);
;             __builtin_amdgcn_fence(__ATOMIC_ACQUIRE, "agent");
.LBB0_1676:
	s_or_b64 exec, exec, s[8:9]
	v_cvt_f32_u32_e32 v4, v2
	s_waitcnt vmcnt(0)
	v_readfirstlane_b32 s6, v3
	v_sub_u32_e32 v3, 0, v2
	v_rcp_iflag_f32_e32 v4, v4
	v_add_u32_e32 v5, s6, v1
	v_mul_f32_e32 v4, 0x4f7ffffe, v4
	v_cvt_u32_f32_e32 v4, v4
	v_mul_lo_u32 v1, v3, v4
	v_mul_hi_u32 v1, v4, v1
	v_add_u32_e32 v1, v4, v1
	v_mul_hi_u32 v1, v5, v1
	v_mul_lo_u32 v3, v1, v2
	v_sub_u32_e32 v3, v5, v3
	v_add_u32_e32 v4, 1, v1
	v_cmp_ge_u32_e32 vcc, v3, v2
	s_nop 1
	v_cndmask_b32_e32 v1, v1, v4, vcc
	v_sub_u32_e32 v4, v3, v2
	v_cndmask_b32_e32 v3, v3, v4, vcc
	v_add_u32_e32 v4, 1, v1
	v_cmp_ge_u32_e32 vcc, v3, v2
	v_add_u32_e32 v3, 1, v5
	s_nop 0
	v_cndmask_b32_e32 v1, v1, v4, vcc
	v_mul_lo_u32 v4, v2, v1
	v_add_u32_e32 v2, v4, v2
	v_cmp_ne_u32_e32 vcc, v3, v2
	s_and_saveexec_b64 s[6:7], vcc
	s_xor_b64 s[6:7], exec, s[6:7]
	s_cbranch_execz .LBB0_1690
	s_waitcnt lgkmcnt(0)
	v_mov_b32_e32 v0, 0x7100
	global_load_dword v0, v0, s[78:79] offset:1024 sc1
	s_add_u32 s12, s78, 0x7500
	s_addc_u32 s13, s79, 0
	s_waitcnt vmcnt(0)
	v_cmp_eq_u32_e32 vcc, v0, v1
	s_and_saveexec_b64 s[8:9], vcc
	s_cbranch_execz .LBB0_1689
	s_add_u32 s10, s78, 0x4200
	s_addc_u32 s11, s79, 0
	s_mov_b32 s24, 1
	s_mov_b64 s[14:15], 0
	v_mov_b32_e32 v0, 0
	s_branch .LBB0_1680
